# proj GEMM K-loop rewritten by hand: software-pipelined LDS fragment double-buffering, LDS writes and global loads interleaved between MFMAs, two staging register sets (prefetch distance 2 tiles), runn
# speedup vs baseline: 1.0120x; 1.0120x over previous
; DI int opaque_tid() { int t = threadIdx.x; asm volatile("" : "+v"(t)); return t; }
; #define G_LOAD(KOFF) do { rw0 = *(const uint4*)(gw + (KOFF)); rw1 = *(const uint4*)(gw1 + (KOFF)); rw2 = *(const uint4*)(gw2 + (KOFF)); rw3 = *(const uint4*)(gw3 + (KOFF)); \
;                           rx0 = *(const uint4*)(gx + (KOFF)); rx1 = *(const uint4*)(gx1 + (KOFF)); rx2 = *(const uint4*)(gx2 + (KOFF)); rx3 = *(const uint4*)(gx3 + (KOFF)); } while (0)
; DI void gemm128(const u16* __restrict__ W, int ldw, const u16* __restrict__ X, int ldx, int K, f32x16 (&acc)[2][2], char* smem) {
;     ...
;   const int tid = opaque_tid(), lane = tid & 63, wave = __builtin_amdgcn_readfirstlane(tid >> 6), r = lane & 31, h = lane >> 5;
;   const int wn = wave & 1, wm = wave >> 1;
;   const int lc = tid & 7, lr = tid >> 3;
;   const u16* gw = W + (size_t)lr * ldw + lc * 8;
;   const u16* gx = X + (size_t)lr * ldx + lc * 8;
;   const u16* gw1 = gw + (size_t)32 * ldw; const u16* gw2 = gw + (size_t)64 * ldw; const u16* gw3 = gw + (size_t)96 * ldw;
;   const u16* gx1 = gx + (size_t)32 * ldx; const u16* gx2 = gx + (size_t)64 * ldx; const u16* gx3 = gx + (size_t)96 * ldx;
;   uint4 rw0, rw1, rw2, rw3, rx0, rx1, rx2, rx3;
;     ...
;   G_LOAD(0);
;   G_STORE(0);
;   const int nk = K >> 6;
;   G_LOAD(64);
; DI void phase_proj(const Params& p, int layer, char* smem, int xcd, int loc, int nloc) {
;     ...
; #pragma unroll
;     for (int mi = 0; mi < 2; ++mi) {
;       const float4* sp = (const float4*)(XSS + (size_t)(m0 + wm * 64 + mi * 32 + r) * 16);
;       float4 q0 = sp[0], q1 = sp[1], q2 = sp[2], q3 = sp[3];
;       float ss = ((q0.x + q0.y) + (q0.z + q0.w)) + ((q1.x + q1.y) + (q1.z + q1.w)) + ((q2.x + q2.y) + (q2.z + q2.w)) + ((q3.x + q3.y) + (q3.z + q3.w));
;       rinv2[mi] = rsqrtf(ss * (1.f / 1024.f) + EPS);
;     }
;     gemm128(WT + (size_t)n0 * LDX, LDX, XB + (size_t)m0 * LDX, LDX, 1024, acc, smem);
.LBB0_1414:
	s_lshl_b32 s10, s41, 7
	v_add_u32_e32 v20, s10, v106
	v_ashrrev_i32_e32 v21, 31, v20
	v_readlane_b32 s18, v252, 36
	v_lshlrev_b64 v[4:5], 6, v[20:21]
	v_readlane_b32 s19, v252, 37
	v_or_b32_e32 v20, 32, v20
	v_ashrrev_i32_e32 v21, 31, v20
	v_lshl_add_u64 v[16:17], s[18:19], 0, v[4:5]
	global_load_dwordx4 v[4:7], v[16:17], off
	global_load_dwordx4 v[8:11], v[16:17], off offset:16
	global_load_dwordx4 v[12:15], v[16:17], off offset:32
	s_lshl_b32 s15, s50, 7
	global_load_dwordx4 v[16:19], v[16:17], off offset:48
	s_mul_i32 s7, s50, 0x44000
	v_lshlrev_b64 v[20:21], 6, v[20:21]
	s_mul_hi_i32 s11, s15, 0x880
	s_add_u32 s12, s5, s7
	v_lshl_add_u64 v[32:33], s[18:19], 0, v[20:21]
	v_mov_b32_e32 v104, v128
	s_addc_u32 s13, s30, s11
	global_load_dwordx4 v[20:23], v[32:33], off offset:16
	global_load_dwordx4 v[24:27], v[32:33], off
	v_mov_b64_e32 v[36:37], s[12:13]
	global_load_dwordx4 v[28:31], v[32:33], off offset:32
	s_nop 0
	global_load_dwordx4 v[32:35], v[32:33], off offset:48
	v_mov_b32_e32 v69, v3
	v_ashrrev_i32_e32 v105, 3, v104
	v_lshlrev_b32_e32 v40, 4, v104
	v_mad_i64_i32 v[36:37], s[12:13], v105, s24, v[36:37]
	v_and_b32_e32 v68, 0x70, v40
	v_lshl_add_u64 v[102:103], v[36:37], 0, v[68:69]
	s_mul_i32 s6, s41, 0x44000
	v_add_co_u32_e32 v72, vcc, s38, v102
	s_mul_hi_i32 s7, s10, 0x880
	s_add_u32 s18, s22, s6
	v_addc_co_u32_e32 v73, vcc, 0, v103, vcc
	s_addc_u32 s19, s23, s7
	v_add_co_u32_e32 v76, vcc, s39, v102
	v_mov_b64_e32 v[38:39], s[18:19]
	s_nop 0
	v_addc_co_u32_e32 v77, vcc, 0, v103, vcc
	v_mad_i64_i32 v[38:39], s[12:13], v105, s24, v[38:39]
	v_add_co_u32_e32 v80, vcc, s42, v102
	v_lshl_add_u64 v[84:85], v[38:39], 0, v[68:69]
	s_nop 0
	v_addc_co_u32_e32 v81, vcc, 0, v103, vcc
	v_add_co_u32_e32 v88, vcc, s38, v84
	global_load_dwordx4 v[36:39], v[102:103], off
	global_load_dwordx4 v[40:43], v[84:85], off
	v_addc_co_u32_e32 v89, vcc, 0, v85, vcc
	v_add_co_u32_e32 v92, vcc, s39, v84
	global_load_dwordx4 v[44:47], v[72:73], off
	global_load_dwordx4 v[48:51], v[76:77], off
	global_load_dwordx4 v[52:55], v[80:81], off
	v_addc_co_u32_e32 v93, vcc, 0, v85, vcc
	v_add_co_u32_e32 v96, vcc, s42, v84
	global_load_dwordx4 v[56:59], v[88:89], off
	global_load_dwordx4 v[60:63], v[92:93], off
	v_addc_co_u32_e32 v97, vcc, 0, v85, vcc
	global_load_dwordx4 v[64:67], v[96:97], off
	v_mad_u64_u32 v[100:101], s[12:13], v105, s2, v[68:69]
	global_load_dwordx4 v[80:83], v[80:81], off offset:128
	s_mov_b32 s11, 0x800000
	global_load_dwordx4 v[84:87], v[84:85], off offset:128
	v_readfirstlane_b32 s14, v104
	global_load_dwordx4 v[88:91], v[88:89], off offset:128
	s_lshr_b32 s12, s14, 1
	global_load_dwordx4 v[92:95], v[92:93], off offset:128
	s_and_b32 s16, s14, 64
	s_and_b32 s12, s12, 0xfffffc0
	s_mulk_i32 s16, 0x90
	s_mulk_i32 s12, 0x90
	global_load_dwordx4 v[76:79], v[76:77], off offset:128
	s_waitcnt vmcnt(20)
	v_mov_b32_e32 v70, v5
	v_mov_b32_e32 v71, v6
	s_waitcnt vmcnt(19)
	v_mov_b32_e32 v74, v9
	v_mov_b32_e32 v75, v10
	v_mov_b32_e32 v5, v7
	v_mov_b32_e32 v9, v11
	v_pk_add_f32 v[4:5], v[70:71], v[4:5]
	v_pk_add_f32 v[8:9], v[74:75], v[8:9]
	global_load_dwordx4 v[68:71], v[102:103], off offset:128
	s_waitcnt vmcnt(19)
	v_mov_b32_e32 v6, v13
	global_load_dwordx4 v[72:75], v[72:73], off offset:128
	v_mov_b32_e32 v10, v15
	global_load_dwordx4 v[96:99], v[96:97], off offset:128
	v_pk_add_f32 v[6:7], v[12:13], v[6:7]
	v_pk_add_f32 v[10:11], v[14:15], v[10:11]
	v_pk_add_f32 v[4:5], v[4:5], v[4:5] op_sel:[0,1] op_sel_hi:[1,0]
	v_pk_add_f32 v[8:9], v[8:9], v[8:9] op_sel:[0,1] op_sel_hi:[1,0]
	s_waitcnt vmcnt(20)
	v_mov_b32_e32 v7, v18
	v_mov_b32_e32 v5, v16
	v_mov_b32_e32 v9, v17
	v_mov_b32_e32 v11, v19
	v_pk_add_f32 v[4:5], v[4:5], v[8:9]
	v_pk_add_f32 v[6:7], v[6:7], v[10:11]
	s_waitcnt vmcnt(17)
	v_mov_b32_e32 v8, v29
	v_pk_add_f32 v[4:5], v[4:5], v[6:7]
	v_mov_b32_e32 v6, v21
	v_add_f32_e32 v4, v4, v5
	v_fmamk_f32 v4, v4, 0x3a800000, v206
	v_mul_f32_e32 v5, 0x4b800000, v4
	v_cmp_gt_f32_e64 s[46:47], s11, v4
	v_mov_b32_e32 v7, v22
	v_mov_b32_e32 v21, v23
	v_cndmask_b32_e64 v4, v4, v5, s[46:47]
	v_rsq_f32_e32 v119, v4
	v_mov_b32_e32 v4, v25
	v_mov_b32_e32 v5, v26
	v_mov_b32_e32 v25, v27
	v_pk_add_f32 v[4:5], v[4:5], v[24:25]
	v_pk_add_f32 v[6:7], v[6:7], v[20:21]
	v_mov_b32_e32 v10, v31
	v_pk_add_f32 v[4:5], v[4:5], v[4:5] op_sel:[0,1] op_sel_hi:[1,0]
	v_pk_add_f32 v[6:7], v[6:7], v[6:7] op_sel:[0,1] op_sel_hi:[1,0]
	v_pk_add_f32 v[8:9], v[28:29], v[8:9]
	v_pk_add_f32 v[10:11], v[30:31], v[10:11]
	s_waitcnt vmcnt(16)
	v_mov_b32_e32 v5, v32
	v_mov_b32_e32 v7, v33
	v_mov_b32_e32 v9, v34
	v_mov_b32_e32 v11, v35
	v_pk_add_f32 v[4:5], v[4:5], v[6:7]
	v_pk_add_f32 v[6:7], v[8:9], v[10:11]
	s_waitcnt vmcnt(15)
	ds_write_b128 v100, v[36:39]
	v_pk_add_f32 v[4:5], v[4:5], v[6:7]
	v_and_b32_e32 v6, 7, v104
	v_add_f32_e32 v4, v4, v5
	v_fmamk_f32 v4, v4, 0x3a800000, v206
	v_mul_f32_e32 v5, 0x4b800000, v4
	v_cmp_gt_f32_e64 s[44:45], s11, v4
	s_mov_b32 s11, 0
	s_waitcnt vmcnt(13)
	ds_write_b128 v100, v[44:47] offset:4608
	v_cndmask_b32_e64 v4, v4, v5, s[44:45]
	v_rsq_f32_e32 v118, v4
	v_and_b32_e32 v4, 31, v104
	v_lshrrev_b32_e32 v5, 1, v104
	v_mul_u32_u24_e32 v4, 0x90, v4
	v_and_b32_e32 v5, 16, v5
	v_add3_u32 v101, s16, v4, v5
	v_add3_u32 v120, s12, v4, v5
	v_mov_b64_e32 v[4:5], s[6:7]
	v_mad_i64_i32 v[4:5], s[6:7], v105, s24, v[4:5]
	v_lshl_or_b32 v4, v6, 4, v4
	v_lshl_add_u64 v[104:105], s[94:95], 0, v[4:5]
	v_mov_b32_e32 v4, 0
	s_waitcnt vmcnt(12)
	ds_write_b128 v100, v[48:51] offset:9216
	s_waitcnt vmcnt(11)
	ds_write_b128 v100, v[52:55] offset:13824
	ds_write_b128 v100, v[40:43] offset:36864
	s_waitcnt vmcnt(10)
	ds_write_b128 v100, v[56:59] offset:41472
	s_waitcnt vmcnt(9)
; #define MFMA32(a, b, c) __builtin_amdgcn_mfma_f32_32x32x16_bf16((a), (b), (c), 0, 0, 0)
; #define G_LOAD(KOFF) do { rw0 = *(const uint4*)(gw + (KOFF)); rw1 = *(const uint4*)(gw1 + (KOFF)); rw2 = *(const uint4*)(gw2 + (KOFF)); rw3 = *(const uint4*)(gw3 + (KOFF)); \
;                           rx0 = *(const uint4*)(gx + (KOFF)); rx1 = *(const uint4*)(gx1 + (KOFF)); rx2 = *(const uint4*)(gx2 + (KOFF)); rx3 = *(const uint4*)(gx3 + (KOFF)); } while (0)
; DI void gemm128(const u16* __restrict__ W, int ldw, const u16* __restrict__ X, int ldx, int K, f32x16 (&acc)[2][2], char* smem) {
;     ...
;   G_LOAD(0);
;   G_STORE(0);
;   const int nk = K >> 6;
;   G_LOAD(64);
;   __syncthreads();
;   for (int kt = 0; kt < nk; ++kt) {
;     const int buf = kt & 1;
; #pragma unroll
;     for (int ks = 0; ks < 4; ++ks) {
;       bf16x8 a0 = *(const bf16x8*)&sw[buf][wn * 64 + r][ks * 16 + h * 8];
;       bf16x8 a1 = *(const bf16x8*)&sw[buf][wn * 64 + 32 + r][ks * 16 + h * 8];
;       bf16x8 b0 = *(const bf16x8*)&sx[buf][wm * 64 + r][ks * 16 + h * 8];
;       bf16x8 b1 = *(const bf16x8*)&sx[buf][wm * 64 + 32 + r][ks * 16 + h * 8];
;       acc[0][0] = MFMA32(a0, b0, acc[0][0]);
;       acc[0][1] = MFMA32(a0, b1, acc[0][1]);
;       acc[1][0] = MFMA32(a1, b0, acc[1][0]);
;       acc[1][1] = MFMA32(a1, b1, acc[1][1]);
;     }
;     if (kt + 1 < nk) G_STORE(buf ^ 1);
;     if (kt + 2 < nk) G_LOAD((kt + 2) * 64);
;     __syncthreads();
;   }
	ds_write_b128 v100, v[60:63] offset:46080
	s_waitcnt vmcnt(8)
	ds_write_b128 v100, v[64:67] offset:50688
	s_mov_b64 s[6:7], 0
	v_mov_b32_e32 v5, v4
	v_mov_b32_e32 v6, v4
	v_mov_b32_e32 v7, v4
	v_mov_b32_e32 v8, v4
	v_mov_b32_e32 v9, v4
	v_mov_b32_e32 v10, v4
	v_mov_b32_e32 v11, v4
	v_mov_b32_e32 v12, v4
	v_mov_b32_e32 v13, v4
	v_mov_b32_e32 v14, v4
	v_mov_b32_e32 v15, v4
	v_mov_b32_e32 v16, v4
	v_mov_b32_e32 v17, v4
	v_mov_b32_e32 v18, v4
	v_mov_b32_e32 v19, v4
	v_mov_b32_e32 v36, v4
	v_mov_b32_e32 v37, v4
	v_mov_b32_e32 v38, v4
	v_mov_b32_e32 v39, v4
	v_mov_b32_e32 v40, v4
	v_mov_b32_e32 v41, v4
	v_mov_b32_e32 v42, v4
	v_mov_b32_e32 v43, v4
	v_mov_b32_e32 v44, v4
	v_mov_b32_e32 v45, v4
	v_mov_b32_e32 v46, v4
	v_mov_b32_e32 v47, v4
	v_mov_b32_e32 v48, v4
	v_mov_b32_e32 v49, v4
	v_mov_b32_e32 v50, v4
	v_mov_b32_e32 v51, v4
	v_mov_b32_e32 v20, v4
	v_mov_b32_e32 v21, v4
	v_mov_b32_e32 v22, v4
	v_mov_b32_e32 v23, v4
	v_mov_b32_e32 v24, v4
	v_mov_b32_e32 v25, v4
	v_mov_b32_e32 v26, v4
	v_mov_b32_e32 v27, v4
	v_mov_b32_e32 v28, v4
	v_mov_b32_e32 v29, v4
	v_mov_b32_e32 v30, v4
	v_mov_b32_e32 v31, v4
	v_mov_b32_e32 v32, v4
	v_mov_b32_e32 v33, v4
	v_mov_b32_e32 v34, v4
	v_mov_b32_e32 v35, v4
	v_mov_b32_e32 v52, v4
	v_mov_b32_e32 v53, v4
	v_mov_b32_e32 v54, v4
	v_mov_b32_e32 v55, v4
	v_mov_b32_e32 v56, v4
	v_mov_b32_e32 v57, v4
	v_mov_b32_e32 v58, v4
	v_mov_b32_e32 v59, v4
	v_mov_b32_e32 v60, v4
	v_mov_b32_e32 v61, v4
	v_mov_b32_e32 v62, v4
	v_mov_b32_e32 v63, v4
	v_mov_b32_e32 v64, v4
	v_mov_b32_e32 v65, v4
	v_mov_b32_e32 v66, v4
	v_mov_b32_e32 v67, v4
	s_waitcnt lgkmcnt(0)
	s_barrier
	v_mov_b32_e32 v178, v102
	v_mov_b32_e32 v179, v103
	v_add_co_u32_e32 v180, vcc, s38, v102
	s_nop 1
	v_addc_co_u32_e32 v181, vcc, 0, v103, vcc
	v_add_co_u32_e32 v182, vcc, s39, v102
	s_nop 1
	v_addc_co_u32_e32 v183, vcc, 0, v103, vcc
	v_add_co_u32_e32 v184, vcc, s42, v102
	s_nop 1
	v_addc_co_u32_e32 v185, vcc, 0, v103, vcc
	v_add_co_u32_e32 v186, vcc, s43, v104
	s_mov_b32 s12, 0x2ba9000
	s_nop 0
	v_addc_co_u32_e32 v187, vcc, 0, v105, vcc
	v_add_co_u32_e32 v188, vcc, s12, v104
	s_mov_b32 s12, 0x2bba000
	s_nop 0
	v_addc_co_u32_e32 v189, vcc, 0, v105, vcc
	v_add_co_u32_e32 v190, vcc, s12, v104
	s_mov_b32 s12, 0x2bcb000
	s_nop 0
	v_addc_co_u32_e32 v191, vcc, 0, v105, vcc
	v_add_co_u32_e32 v192, vcc, s12, v104
	s_nop 1
	v_addc_co_u32_e32 v193, vcc, 0, v105, vcc
	s_movk_i32 s6, 0x80
	s_mov_b32 s7, 0
	global_load_dwordx4 v[174:177], v[178:179], off offset:256
	global_load_dwordx4 v[194:197], v[180:181], off offset:256
	global_load_dwordx4 v[198:201], v[182:183], off offset:256
	global_load_dwordx4 v[230:233], v[184:185], off offset:256
	global_load_dwordx4 v[240:243], v[186:187], off offset:256
	global_load_dwordx4 v[244:247], v[188:189], off offset:256
	global_load_dwordx4 v[248:251], v[190:191], off offset:256
	global_load_dwordx4 v[102:105], v[192:193], off offset:256
	ds_read_b128 v[154:157], v101
	ds_read_b128 v[162:165], v120 offset:36864
	ds_read_b128 v[150:153], v120 offset:41472
	ds_read_b128 v[122:125], v101 offset:4608
.Lproj_kloop:
	s_and_b32 s12, s11, 1
	s_mul_i32 s13, s12, 0x4800
	s_xor_b32 s12, s12, 1
	s_mulk_i32 s12, 0x4800
	v_add_u32_e32 v121, s13, v101
	v_add_u32_e32 v126, s13, v120
	v_add_u32_e32 v234, s12, v100
	v_add_u32_e32 v235, s12, v101
	v_add_u32_e32 v239, s12, v120
	ds_read_b128 v[158:161], v121 offset:32
	ds_read_b128 v[166:169], v126 offset:36896
	ds_read_b128 v[170:173], v126 offset:41504
	ds_read_b128 v[130:133], v121 offset:4640
	s_waitcnt lgkmcnt(6)
	v_mfma_f32_32x32x16_bf16 v[52:67], v[154:157], v[162:165], v[52:67]
	s_waitcnt vmcnt(8)
	ds_write_b128 v234, v[68:71]
	ds_write_b128 v234, v[72:75] offset:4608
	global_load_dwordx4 v[68:71], v[178:179], off offset:384
	global_load_dwordx4 v[72:75], v[180:181], off offset:384
	s_waitcnt lgkmcnt(7)
	v_mfma_f32_32x32x16_bf16 v[20:35], v[154:157], v[150:153], v[20:35]
	ds_write_b128 v234, v[76:79] offset:9216
	ds_write_b128 v234, v[80:83] offset:13824
	global_load_dwordx4 v[76:79], v[182:183], off offset:384
	global_load_dwordx4 v[80:83], v[184:185], off offset:384
	s_waitcnt lgkmcnt(8)
	v_mfma_f32_32x32x16_bf16 v[36:51], v[122:125], v[162:165], v[36:51]
	ds_write_b128 v234, v[84:87] offset:36864
	ds_write_b128 v234, v[88:91] offset:41472
	global_load_dwordx4 v[84:87], v[186:187], off offset:384
	global_load_dwordx4 v[88:91], v[188:189], off offset:384
	v_mfma_f32_32x32x16_bf16 v[4:19], v[122:125], v[150:153], v[4:19]
	ds_write_b128 v234, v[92:95] offset:46080
	ds_write_b128 v234, v[96:99] offset:50688
	global_load_dwordx4 v[92:95], v[190:191], off offset:384
	global_load_dwordx4 v[96:99], v[192:193], off offset:384
	ds_read_b128 v[154:157], v121 offset:64
	ds_read_b128 v[162:165], v126 offset:36928
	ds_read_b128 v[150:153], v126 offset:41536
	ds_read_b128 v[122:125], v121 offset:4672
	s_waitcnt lgkmcnt(14)
	v_mfma_f32_32x32x16_bf16 v[52:67], v[158:161], v[166:169], v[52:67]
	s_waitcnt lgkmcnt(13)
	v_mfma_f32_32x32x16_bf16 v[20:35], v[158:161], v[170:173], v[20:35]
	s_waitcnt lgkmcnt(12)
	v_mfma_f32_32x32x16_bf16 v[36:51], v[130:133], v[166:169], v[36:51]
	v_mfma_f32_32x32x16_bf16 v[4:19], v[130:133], v[170:173], v[4:19]
	ds_read_b128 v[158:161], v121 offset:96
	ds_read_b128 v[166:169], v126 offset:36960
	ds_read_b128 v[170:173], v126 offset:41568
	ds_read_b128 v[130:133], v121 offset:4704
	s_waitcnt lgkmcnt(6)
	v_mfma_f32_32x32x16_bf16 v[52:67], v[154:157], v[162:165], v[52:67]
	v_lshl_add_u64 v[178:179], v[178:179], 0, s[6:7]
	v_lshl_add_u64 v[180:181], v[180:181], 0, s[6:7]
	v_lshl_add_u64 v[182:183], v[182:183], 0, s[6:7]
	s_waitcnt lgkmcnt(5)
	v_mfma_f32_32x32x16_bf16 v[20:35], v[154:157], v[150:153], v[20:35]
	v_lshl_add_u64 v[184:185], v[184:185], 0, s[6:7]
	v_lshl_add_u64 v[186:187], v[186:187], 0, s[6:7]
	v_lshl_add_u64 v[188:189], v[188:189], 0, s[6:7]
	s_waitcnt lgkmcnt(4)
	v_mfma_f32_32x32x16_bf16 v[36:51], v[122:125], v[162:165], v[36:51]
	v_lshl_add_u64 v[190:191], v[190:191], 0, s[6:7]
	v_lshl_add_u64 v[192:193], v[192:193], 0, s[6:7]
	v_mfma_f32_32x32x16_bf16 v[4:19], v[122:125], v[150:153], v[4:19]
	s_add_i32 s11, s11, 1
	s_waitcnt lgkmcnt(0)
	s_barrier
; #define MFMA32(a, b, c) __builtin_amdgcn_mfma_f32_32x32x16_bf16((a), (b), (c), 0, 0, 0)
; #define G_LOAD(KOFF) do { rw0 = *(const uint4*)(gw + (KOFF)); rw1 = *(const uint4*)(gw1 + (KOFF)); rw2 = *(const uint4*)(gw2 + (KOFF)); rw3 = *(const uint4*)(gw3 + (KOFF)); \
;                           rx0 = *(const uint4*)(gx + (KOFF)); rx1 = *(const uint4*)(gx1 + (KOFF)); rx2 = *(const uint4*)(gx2 + (KOFF)); rx3 = *(const uint4*)(gx3 + (KOFF)); } while (0)
; DI void gemm128(const u16* __restrict__ W, int ldw, const u16* __restrict__ X, int ldx, int K, f32x16 (&acc)[2][2], char* smem) {
;     ...
;   for (int kt = 0; kt < nk; ++kt) {
;     const int buf = kt & 1;
; #pragma unroll
;     for (int ks = 0; ks < 4; ++ks) {
;       bf16x8 a0 = *(const bf16x8*)&sw[buf][wn * 64 + r][ks * 16 + h * 8];
;       bf16x8 a1 = *(const bf16x8*)&sw[buf][wn * 64 + 32 + r][ks * 16 + h * 8];
;       bf16x8 b0 = *(const bf16x8*)&sx[buf][wm * 64 + r][ks * 16 + h * 8];
;       bf16x8 b1 = *(const bf16x8*)&sx[buf][wm * 64 + 32 + r][ks * 16 + h * 8];
;       acc[0][0] = MFMA32(a0, b0, acc[0][0]);
;       acc[0][1] = MFMA32(a0, b1, acc[0][1]);
;       acc[1][0] = MFMA32(a1, b0, acc[1][0]);
;       acc[1][1] = MFMA32(a1, b1, acc[1][1]);
;     }
;     if (kt + 1 < nk) G_STORE(buf ^ 1);
;     if (kt + 2 < nk) G_LOAD((kt + 2) * 64);
;     __syncthreads();
;   }
	ds_read_b128 v[154:157], v235
	ds_read_b128 v[162:165], v239 offset:36864
	ds_read_b128 v[150:153], v239 offset:41472
	ds_read_b128 v[122:125], v235 offset:4608
	v_mfma_f32_32x32x16_bf16 v[52:67], v[158:161], v[166:169], v[52:67]
	v_mfma_f32_32x32x16_bf16 v[20:35], v[158:161], v[170:173], v[20:35]
	v_mfma_f32_32x32x16_bf16 v[36:51], v[130:133], v[166:169], v[36:51]
	v_mfma_f32_32x32x16_bf16 v[4:19], v[130:133], v[170:173], v[4:19]
	s_and_b32 s12, s11, 1
	s_mul_i32 s13, s12, 0x4800
	s_xor_b32 s12, s12, 1
	s_mulk_i32 s12, 0x4800
	v_add_u32_e32 v121, s13, v101
	v_add_u32_e32 v126, s13, v120
	v_add_u32_e32 v234, s12, v100
	v_add_u32_e32 v235, s12, v101
	v_add_u32_e32 v239, s12, v120
	ds_read_b128 v[158:161], v121 offset:32
	ds_read_b128 v[166:169], v126 offset:36896
	ds_read_b128 v[170:173], v126 offset:41504
	ds_read_b128 v[130:133], v121 offset:4640
	s_waitcnt lgkmcnt(6)
	v_mfma_f32_32x32x16_bf16 v[52:67], v[154:157], v[162:165], v[52:67]
	s_waitcnt vmcnt(8)
	ds_write_b128 v234, v[174:177]
	ds_write_b128 v234, v[194:197] offset:4608
	global_load_dwordx4 v[174:177], v[178:179], off offset:384
	global_load_dwordx4 v[194:197], v[180:181], off offset:384
	s_waitcnt lgkmcnt(7)
	v_mfma_f32_32x32x16_bf16 v[20:35], v[154:157], v[150:153], v[20:35]
	ds_write_b128 v234, v[198:201] offset:9216
	ds_write_b128 v234, v[230:233] offset:13824
	global_load_dwordx4 v[198:201], v[182:183], off offset:384
	global_load_dwordx4 v[230:233], v[184:185], off offset:384
	s_waitcnt lgkmcnt(8)
	v_mfma_f32_32x32x16_bf16 v[36:51], v[122:125], v[162:165], v[36:51]
	ds_write_b128 v234, v[240:243] offset:36864
	ds_write_b128 v234, v[244:247] offset:41472
	global_load_dwordx4 v[240:243], v[186:187], off offset:384
	global_load_dwordx4 v[244:247], v[188:189], off offset:384
	v_mfma_f32_32x32x16_bf16 v[4:19], v[122:125], v[150:153], v[4:19]
	ds_write_b128 v234, v[248:251] offset:46080
	ds_write_b128 v234, v[102:105] offset:50688
	global_load_dwordx4 v[248:251], v[190:191], off offset:384
	global_load_dwordx4 v[102:105], v[192:193], off offset:384
	ds_read_b128 v[154:157], v121 offset:64
	ds_read_b128 v[162:165], v126 offset:36928
	ds_read_b128 v[150:153], v126 offset:41536
	ds_read_b128 v[122:125], v121 offset:4672
	s_waitcnt lgkmcnt(14)
	v_mfma_f32_32x32x16_bf16 v[52:67], v[158:161], v[166:169], v[52:67]
	s_waitcnt lgkmcnt(13)
	v_mfma_f32_32x32x16_bf16 v[20:35], v[158:161], v[170:173], v[20:35]
	s_waitcnt lgkmcnt(12)
	v_mfma_f32_32x32x16_bf16 v[36:51], v[130:133], v[166:169], v[36:51]
	v_mfma_f32_32x32x16_bf16 v[4:19], v[130:133], v[170:173], v[4:19]
	ds_read_b128 v[158:161], v121 offset:96
	ds_read_b128 v[166:169], v126 offset:36960
	ds_read_b128 v[170:173], v126 offset:41568
	ds_read_b128 v[130:133], v121 offset:4704
	s_waitcnt lgkmcnt(6)
	v_mfma_f32_32x32x16_bf16 v[52:67], v[154:157], v[162:165], v[52:67]
	v_lshl_add_u64 v[178:179], v[178:179], 0, s[6:7]
	v_lshl_add_u64 v[180:181], v[180:181], 0, s[6:7]
	v_lshl_add_u64 v[182:183], v[182:183], 0, s[6:7]
	s_waitcnt lgkmcnt(5)
	v_mfma_f32_32x32x16_bf16 v[20:35], v[154:157], v[150:153], v[20:35]
	v_lshl_add_u64 v[184:185], v[184:185], 0, s[6:7]
	v_lshl_add_u64 v[186:187], v[186:187], 0, s[6:7]
	v_lshl_add_u64 v[188:189], v[188:189], 0, s[6:7]
	s_waitcnt lgkmcnt(4)
	v_mfma_f32_32x32x16_bf16 v[36:51], v[122:125], v[162:165], v[36:51]
	v_lshl_add_u64 v[190:191], v[190:191], 0, s[6:7]
	v_lshl_add_u64 v[192:193], v[192:193], 0, s[6:7]
	v_mfma_f32_32x32x16_bf16 v[4:19], v[122:125], v[150:153], v[4:19]
	s_add_i32 s11, s11, 1
	s_waitcnt lgkmcnt(0)
	s_barrier
	ds_read_b128 v[154:157], v235
	ds_read_b128 v[162:165], v239 offset:36864
	ds_read_b128 v[150:153], v239 offset:41472
	ds_read_b128 v[122:125], v235 offset:4608
	v_mfma_f32_32x32x16_bf16 v[52:67], v[158:161], v[166:169], v[52:67]
	v_mfma_f32_32x32x16_bf16 v[20:35], v[158:161], v[170:173], v[20:35]
	v_mfma_f32_32x32x16_bf16 v[36:51], v[130:133], v[166:169], v[36:51]
	v_mfma_f32_32x32x16_bf16 v[4:19], v[130:133], v[170:173], v[4:19]
	s_cmp_lt_u32 s11, 12
	s_cbranch_scc1 .Lproj_kloop
	s_and_b32 s12, s11, 1
	s_mul_i32 s13, s12, 0x4800
	s_xor_b32 s12, s12, 1
	s_mulk_i32 s12, 0x4800
	v_add_u32_e32 v121, s13, v101
	v_add_u32_e32 v126, s13, v120
	v_add_u32_e32 v234, s12, v100
	v_add_u32_e32 v235, s12, v101
	v_add_u32_e32 v239, s12, v120
	ds_read_b128 v[158:161], v121 offset:32
	ds_read_b128 v[166:169], v126 offset:36896
	ds_read_b128 v[170:173], v126 offset:41504
	ds_read_b128 v[130:133], v121 offset:4640
	s_waitcnt lgkmcnt(6)
	v_mfma_f32_32x32x16_bf16 v[52:67], v[154:157], v[162:165], v[52:67]
	s_waitcnt vmcnt(8)
	ds_write_b128 v234, v[68:71]
	ds_write_b128 v234, v[72:75] offset:4608
	global_load_dwordx4 v[68:71], v[178:179], off offset:384
	global_load_dwordx4 v[72:75], v[180:181], off offset:384
	s_waitcnt lgkmcnt(7)
	v_mfma_f32_32x32x16_bf16 v[20:35], v[154:157], v[150:153], v[20:35]
	ds_write_b128 v234, v[76:79] offset:9216
	ds_write_b128 v234, v[80:83] offset:13824
	global_load_dwordx4 v[76:79], v[182:183], off offset:384
	global_load_dwordx4 v[80:83], v[184:185], off offset:384
	s_waitcnt lgkmcnt(8)
	v_mfma_f32_32x32x16_bf16 v[36:51], v[122:125], v[162:165], v[36:51]
	ds_write_b128 v234, v[84:87] offset:36864
	ds_write_b128 v234, v[88:91] offset:41472
	global_load_dwordx4 v[84:87], v[186:187], off offset:384
	global_load_dwordx4 v[88:91], v[188:189], off offset:384
	v_mfma_f32_32x32x16_bf16 v[4:19], v[122:125], v[150:153], v[4:19]
	ds_write_b128 v234, v[92:95] offset:46080
	ds_write_b128 v234, v[96:99] offset:50688
	global_load_dwordx4 v[92:95], v[190:191], off offset:384
	global_load_dwordx4 v[96:99], v[192:193], off offset:384
	ds_read_b128 v[154:157], v121 offset:64
	ds_read_b128 v[162:165], v126 offset:36928
	ds_read_b128 v[150:153], v126 offset:41536
	ds_read_b128 v[122:125], v121 offset:4672
	s_waitcnt lgkmcnt(14)
; #define MFMA32(a, b, c) __builtin_amdgcn_mfma_f32_32x32x16_bf16((a), (b), (c), 0, 0, 0)
; #define G_LOAD(KOFF) do { rw0 = *(const uint4*)(gw + (KOFF)); rw1 = *(const uint4*)(gw1 + (KOFF)); rw2 = *(const uint4*)(gw2 + (KOFF)); rw3 = *(const uint4*)(gw3 + (KOFF)); \
;                           rx0 = *(const uint4*)(gx + (KOFF)); rx1 = *(const uint4*)(gx1 + (KOFF)); rx2 = *(const uint4*)(gx2 + (KOFF)); rx3 = *(const uint4*)(gx3 + (KOFF)); } while (0)
; DI void gemm128(const u16* __restrict__ W, int ldw, const u16* __restrict__ X, int ldx, int K, f32x16 (&acc)[2][2], char* smem) {
;     ...
;   for (int kt = 0; kt < nk; ++kt) {
;     const int buf = kt & 1;
; #pragma unroll
;     for (int ks = 0; ks < 4; ++ks) {
;       bf16x8 a0 = *(const bf16x8*)&sw[buf][wn * 64 + r][ks * 16 + h * 8];
;       bf16x8 a1 = *(const bf16x8*)&sw[buf][wn * 64 + 32 + r][ks * 16 + h * 8];
;       bf16x8 b0 = *(const bf16x8*)&sx[buf][wm * 64 + r][ks * 16 + h * 8];
;       bf16x8 b1 = *(const bf16x8*)&sx[buf][wm * 64 + 32 + r][ks * 16 + h * 8];
;       acc[0][0] = MFMA32(a0, b0, acc[0][0]);
;       acc[0][1] = MFMA32(a0, b1, acc[0][1]);
;       acc[1][0] = MFMA32(a1, b0, acc[1][0]);
;       acc[1][1] = MFMA32(a1, b1, acc[1][1]);
;     }
;     if (kt + 1 < nk) G_STORE(buf ^ 1);
;     if (kt + 2 < nk) G_LOAD((kt + 2) * 64);
;     __syncthreads();
;   }
	v_mfma_f32_32x32x16_bf16 v[52:67], v[158:161], v[166:169], v[52:67]
	s_waitcnt lgkmcnt(13)
	v_mfma_f32_32x32x16_bf16 v[20:35], v[158:161], v[170:173], v[20:35]
	s_waitcnt lgkmcnt(12)
	v_mfma_f32_32x32x16_bf16 v[36:51], v[130:133], v[166:169], v[36:51]
	v_mfma_f32_32x32x16_bf16 v[4:19], v[130:133], v[170:173], v[4:19]
	ds_read_b128 v[158:161], v121 offset:96
	ds_read_b128 v[166:169], v126 offset:36960
	ds_read_b128 v[170:173], v126 offset:41568
	ds_read_b128 v[130:133], v121 offset:4704
	s_waitcnt lgkmcnt(6)
	v_mfma_f32_32x32x16_bf16 v[52:67], v[154:157], v[162:165], v[52:67]
	v_lshl_add_u64 v[178:179], v[178:179], 0, s[6:7]
	v_lshl_add_u64 v[180:181], v[180:181], 0, s[6:7]
	v_lshl_add_u64 v[182:183], v[182:183], 0, s[6:7]
	s_waitcnt lgkmcnt(5)
	v_mfma_f32_32x32x16_bf16 v[20:35], v[154:157], v[150:153], v[20:35]
	v_lshl_add_u64 v[184:185], v[184:185], 0, s[6:7]
	v_lshl_add_u64 v[186:187], v[186:187], 0, s[6:7]
	v_lshl_add_u64 v[188:189], v[188:189], 0, s[6:7]
	s_waitcnt lgkmcnt(4)
	v_mfma_f32_32x32x16_bf16 v[36:51], v[122:125], v[162:165], v[36:51]
	v_lshl_add_u64 v[190:191], v[190:191], 0, s[6:7]
	v_lshl_add_u64 v[192:193], v[192:193], 0, s[6:7]
	v_mfma_f32_32x32x16_bf16 v[4:19], v[122:125], v[150:153], v[4:19]
	s_add_i32 s11, s11, 1
	s_waitcnt lgkmcnt(0)
	s_barrier
	ds_read_b128 v[154:157], v235
	ds_read_b128 v[162:165], v239 offset:36864
	ds_read_b128 v[150:153], v239 offset:41472
	ds_read_b128 v[122:125], v235 offset:4608
	v_mfma_f32_32x32x16_bf16 v[52:67], v[158:161], v[166:169], v[52:67]
	v_mfma_f32_32x32x16_bf16 v[20:35], v[158:161], v[170:173], v[20:35]
	v_mfma_f32_32x32x16_bf16 v[36:51], v[130:133], v[166:169], v[36:51]
	v_mfma_f32_32x32x16_bf16 v[4:19], v[130:133], v[170:173], v[4:19]
	s_and_b32 s12, s11, 1
	s_mul_i32 s13, s12, 0x4800
	s_xor_b32 s12, s12, 1
	s_mulk_i32 s12, 0x4800
	v_add_u32_e32 v121, s13, v101
	v_add_u32_e32 v126, s13, v120
	v_add_u32_e32 v234, s12, v100
	v_add_u32_e32 v235, s12, v101
	v_add_u32_e32 v239, s12, v120
	ds_read_b128 v[158:161], v121 offset:32
	ds_read_b128 v[166:169], v126 offset:36896
	ds_read_b128 v[170:173], v126 offset:41504
	ds_read_b128 v[130:133], v121 offset:4640
	s_waitcnt lgkmcnt(6)
	v_mfma_f32_32x32x16_bf16 v[52:67], v[154:157], v[162:165], v[52:67]
	s_waitcnt vmcnt(8)
	ds_write_b128 v234, v[174:177]
	ds_write_b128 v234, v[194:197] offset:4608
	s_waitcnt lgkmcnt(7)
	v_mfma_f32_32x32x16_bf16 v[20:35], v[154:157], v[150:153], v[20:35]
	ds_write_b128 v234, v[198:201] offset:9216
	ds_write_b128 v234, v[230:233] offset:13824
	s_waitcnt lgkmcnt(8)
	v_mfma_f32_32x32x16_bf16 v[36:51], v[122:125], v[162:165], v[36:51]
	ds_write_b128 v234, v[240:243] offset:36864
	ds_write_b128 v234, v[244:247] offset:41472
	v_mfma_f32_32x32x16_bf16 v[4:19], v[122:125], v[150:153], v[4:19]
	ds_write_b128 v234, v[248:251] offset:46080
	ds_write_b128 v234, v[102:105] offset:50688
	ds_read_b128 v[154:157], v121 offset:64
	ds_read_b128 v[162:165], v126 offset:36928
	ds_read_b128 v[150:153], v126 offset:41536
	ds_read_b128 v[122:125], v121 offset:4672
	s_waitcnt lgkmcnt(14)
	v_mfma_f32_32x32x16_bf16 v[52:67], v[158:161], v[166:169], v[52:67]
	s_waitcnt lgkmcnt(13)
	v_mfma_f32_32x32x16_bf16 v[20:35], v[158:161], v[170:173], v[20:35]
	s_waitcnt lgkmcnt(12)
	v_mfma_f32_32x32x16_bf16 v[36:51], v[130:133], v[166:169], v[36:51]
	v_mfma_f32_32x32x16_bf16 v[4:19], v[130:133], v[170:173], v[4:19]
	ds_read_b128 v[158:161], v121 offset:96
	ds_read_b128 v[166:169], v126 offset:36960
	ds_read_b128 v[170:173], v126 offset:41568
	ds_read_b128 v[130:133], v121 offset:4704
	s_waitcnt lgkmcnt(6)
	v_mfma_f32_32x32x16_bf16 v[52:67], v[154:157], v[162:165], v[52:67]
	v_lshl_add_u64 v[178:179], v[178:179], 0, s[6:7]
	v_lshl_add_u64 v[180:181], v[180:181], 0, s[6:7]
	v_lshl_add_u64 v[182:183], v[182:183], 0, s[6:7]
	s_waitcnt lgkmcnt(5)
	v_mfma_f32_32x32x16_bf16 v[20:35], v[154:157], v[150:153], v[20:35]
	v_lshl_add_u64 v[184:185], v[184:185], 0, s[6:7]
	v_lshl_add_u64 v[186:187], v[186:187], 0, s[6:7]
	v_lshl_add_u64 v[188:189], v[188:189], 0, s[6:7]
	s_waitcnt lgkmcnt(4)
	v_mfma_f32_32x32x16_bf16 v[36:51], v[122:125], v[162:165], v[36:51]
	v_lshl_add_u64 v[190:191], v[190:191], 0, s[6:7]
	v_lshl_add_u64 v[192:193], v[192:193], 0, s[6:7]
	v_mfma_f32_32x32x16_bf16 v[4:19], v[122:125], v[150:153], v[4:19]
	s_add_i32 s11, s11, 1
	s_waitcnt lgkmcnt(0)
	s_barrier
; #define MFMA32(a, b, c) __builtin_amdgcn_mfma_f32_32x32x16_bf16((a), (b), (c), 0, 0, 0)
; #define G_LOAD(KOFF) do { rw0 = *(const uint4*)(gw + (KOFF)); rw1 = *(const uint4*)(gw1 + (KOFF)); rw2 = *(const uint4*)(gw2 + (KOFF)); rw3 = *(const uint4*)(gw3 + (KOFF)); \
;                           rx0 = *(const uint4*)(gx + (KOFF)); rx1 = *(const uint4*)(gx1 + (KOFF)); rx2 = *(const uint4*)(gx2 + (KOFF)); rx3 = *(const uint4*)(gx3 + (KOFF)); } while (0)
; DI void gemm128(const u16* __restrict__ W, int ldw, const u16* __restrict__ X, int ldx, int K, f32x16 (&acc)[2][2], char* smem) {
;     ...
;   for (int kt = 0; kt < nk; ++kt) {
;     const int buf = kt & 1;
; #pragma unroll
;     for (int ks = 0; ks < 4; ++ks) {
;       bf16x8 a0 = *(const bf16x8*)&sw[buf][wn * 64 + r][ks * 16 + h * 8];
;       bf16x8 a1 = *(const bf16x8*)&sw[buf][wn * 64 + 32 + r][ks * 16 + h * 8];
;       bf16x8 b0 = *(const bf16x8*)&sx[buf][wm * 64 + r][ks * 16 + h * 8];
;       bf16x8 b1 = *(const bf16x8*)&sx[buf][wm * 64 + 32 + r][ks * 16 + h * 8];
;       acc[0][0] = MFMA32(a0, b0, acc[0][0]);
;       acc[0][1] = MFMA32(a0, b1, acc[0][1]);
;       acc[1][0] = MFMA32(a1, b0, acc[1][0]);
;       acc[1][1] = MFMA32(a1, b1, acc[1][1]);
;     }
;     if (kt + 1 < nk) G_STORE(buf ^ 1);
;     if (kt + 2 < nk) G_LOAD((kt + 2) * 64);
;     __syncthreads();
;   }
; DI void phase_proj(const Params& p, int layer, char* smem, int xcd, int loc, int nloc) {
;     ...
;       const int nb = n0 + wn * 64;
;       const int mb = m0 + wm * 64;
;       const int b = mb >> 12, s0 = mb & 4095;
;       u16 (*st)[72] = (u16 (*)[72])(smem + ((wave & 2) ? 55296 : 18432) + (wave & 1) * 9216);
;       const bool transposed = (nb >= 1024 && nb < 1536) || (nb == N_DSV);
;       const float cs = (nb < 512) ? C_SB : 1.f;
;       u16* dst; size_t rstride;
;       if (nb < 512) { dst = (u16*)(p.ws + WS_QA) + ((size_t)(b * 8 + (nb >> 6)) * 4096 + s0) * 64; rstride = 64; }
;       else if (nb < 1024) { dst = (u16*)(p.ws + WS_KA) + ((size_t)(b * 8 + ((nb - 512) >> 6)) * 4096 + s0) * 64; rstride = 64; }
;       else if (nb < 1536) { dst = VTA + ((size_t)(b * 8 + ((nb - 1024) >> 6)) * 64) * 4096 + s0; rstride = 4096; }
;       else if (nb == N_DSV) { dst = VTC + ((size_t)b * 64) * 4096 + s0; rstride = 4096; }
;       else { dst = PROJ + (size_t)mb * LDP + (nb - 1536); rstride = LDP; }
	v_mfma_f32_32x32x16_bf16 v[52:67], v[158:161], v[166:169], v[52:67]
	v_mfma_f32_32x32x16_bf16 v[20:35], v[158:161], v[170:173], v[20:35]
	v_mfma_f32_32x32x16_bf16 v[36:51], v[130:133], v[166:169], v[36:51]
	v_mfma_f32_32x32x16_bf16 v[4:19], v[130:133], v[170:173], v[4:19]
	ds_read_b128 v[102:105], v101
	ds_read_b128 v[122:125], v120 offset:36864
	ds_read_b128 v[150:153], v120 offset:41472
	s_add_i32 s51, s10, s36
	s_or_b32 s16, s15, s37
	s_ashr_i32 s14, s51, 12
	s_waitcnt lgkmcnt(1)
	v_mfma_f32_32x32x16_bf16 v[52:67], v[102:105], v[122:125], v[52:67]
	s_and_b32 s52, s51, 0xfc0
	s_cmpk_eq_i32 s16, 0x9c0
	s_cselect_b64 s[12:13], -1, 0
	s_cmpk_lg_i32 s16, 0x9c0
	s_cselect_b64 s[18:19], -1, 0
	s_cmpk_lt_i32 s16, 0x200
	s_cselect_b64 s[48:49], -1, 0
	s_waitcnt lgkmcnt(0)
	v_mfma_f32_32x32x16_bf16 v[20:35], v[102:105], v[150:153], v[20:35]
	ds_read_b128 v[102:105], v101 offset:4608
	s_cmpk_gt_i32 s16, 0x1ff
	s_mov_b64 s[28:29], -1
	s_waitcnt lgkmcnt(0)
	v_mfma_f32_32x32x16_bf16 v[36:51], v[102:105], v[122:125], v[36:51]
	v_mfma_f32_32x32x16_bf16 v[4:19], v[102:105], v[150:153], v[4:19]
	ds_read_b128 v[102:105], v101 offset:32
	ds_read_b128 v[122:125], v120 offset:36896
	ds_read_b128 v[150:153], v120 offset:41504
	s_waitcnt lgkmcnt(1)
	v_mfma_f32_32x32x16_bf16 v[52:67], v[102:105], v[122:125], v[52:67]
	s_waitcnt lgkmcnt(0)
	v_mfma_f32_32x32x16_bf16 v[20:35], v[102:105], v[150:153], v[20:35]
	ds_read_b128 v[102:105], v101 offset:4640
	s_waitcnt lgkmcnt(0)
	v_mfma_f32_32x32x16_bf16 v[36:51], v[102:105], v[122:125], v[36:51]
	v_mfma_f32_32x32x16_bf16 v[4:19], v[102:105], v[150:153], v[4:19]
	ds_read_b128 v[102:105], v101 offset:64
	ds_read_b128 v[122:125], v120 offset:36928
	ds_read_b128 v[150:153], v120 offset:41536
	s_waitcnt lgkmcnt(1)
	v_mfma_f32_32x32x16_bf16 v[52:67], v[102:105], v[122:125], v[52:67]
	s_waitcnt lgkmcnt(0)
	v_mfma_f32_32x32x16_bf16 v[20:35], v[102:105], v[150:153], v[20:35]
	ds_read_b128 v[102:105], v101 offset:4672
	s_waitcnt lgkmcnt(0)
	v_mfma_f32_32x32x16_bf16 v[36:51], v[102:105], v[122:125], v[36:51]
	v_mfma_f32_32x32x16_bf16 v[4:19], v[102:105], v[150:153], v[4:19]
	ds_read_b128 v[102:105], v101 offset:96
	ds_read_b128 v[122:125], v120 offset:36960
	ds_read_b128 v[150:153], v120 offset:41568
	s_waitcnt lgkmcnt(1)
	v_mfma_f32_32x32x16_bf16 v[52:67], v[102:105], v[122:125], v[52:67]
	s_waitcnt lgkmcnt(0)
	v_mfma_f32_32x32x16_bf16 v[20:35], v[102:105], v[150:153], v[20:35]
	ds_read_b128 v[102:105], v101 offset:4704
	s_waitcnt vmcnt(7)
	ds_write_b128 v100, v[68:71] offset:18432
	s_waitcnt vmcnt(6)
	ds_write_b128 v100, v[72:75] offset:23040
	s_waitcnt vmcnt(5)
	ds_write_b128 v100, v[76:79] offset:27648
	s_waitcnt vmcnt(4)
	ds_write_b128 v100, v[80:83] offset:32256
	v_add_u32_e32 v68, 0xd800, v100
	s_waitcnt vmcnt(3)
	ds_write_b128 v100, v[84:87] offset:55296
	s_waitcnt vmcnt(2)
	ds_write_b128 v100, v[88:91] offset:59904
	s_waitcnt vmcnt(1)
	ds_write_b128 v100, v[92:95] offset:64512
	s_waitcnt vmcnt(0)
	ds_write_b128 v68, v[96:99] offset:13824
	s_waitcnt lgkmcnt(0)
	s_barrier
	ds_read_b128 v[68:71], v101 offset:18432
	ds_read_b128 v[72:75], v120 offset:55296
	ds_read_b128 v[76:79], v120 offset:59904
	s_waitcnt lgkmcnt(1)
	v_mfma_f32_32x32x16_bf16 v[52:67], v[68:71], v[72:75], v[52:67]
	s_waitcnt lgkmcnt(0)
	v_mfma_f32_32x32x16_bf16 v[20:35], v[68:71], v[76:79], v[20:35]
	ds_read_b128 v[68:71], v101 offset:23040
	v_mfma_f32_32x32x16_bf16 v[36:51], v[102:105], v[122:125], v[36:51]
	v_mfma_f32_32x32x16_bf16 v[4:19], v[102:105], v[150:153], v[4:19]
	s_waitcnt lgkmcnt(0)
	v_mfma_f32_32x32x16_bf16 v[36:51], v[68:71], v[72:75], v[36:51]
	v_mfma_f32_32x32x16_bf16 v[4:19], v[68:71], v[76:79], v[4:19]
	ds_read_b128 v[68:71], v101 offset:18464
	ds_read_b128 v[72:75], v120 offset:55328
	ds_read_b128 v[76:79], v120 offset:59936
	s_waitcnt lgkmcnt(1)
	v_mfma_f32_32x32x16_bf16 v[52:67], v[68:71], v[72:75], v[52:67]
	s_waitcnt lgkmcnt(0)
	v_mfma_f32_32x32x16_bf16 v[20:35], v[68:71], v[76:79], v[20:35]
	ds_read_b128 v[68:71], v101 offset:23072
	s_waitcnt lgkmcnt(0)
	v_mfma_f32_32x32x16_bf16 v[36:51], v[68:71], v[72:75], v[36:51]
	v_mfma_f32_32x32x16_bf16 v[4:19], v[68:71], v[76:79], v[4:19]
	ds_read_b128 v[68:71], v101 offset:18496
	ds_read_b128 v[72:75], v120 offset:55360
	ds_read_b128 v[76:79], v120 offset:59968
	s_waitcnt lgkmcnt(1)
	v_mfma_f32_32x32x16_bf16 v[52:67], v[68:71], v[72:75], v[52:67]
	s_waitcnt lgkmcnt(0)
	v_mfma_f32_32x32x16_bf16 v[20:35], v[68:71], v[76:79], v[20:35]
	ds_read_b128 v[68:71], v101 offset:23104
	s_waitcnt lgkmcnt(0)
	v_mfma_f32_32x32x16_bf16 v[36:51], v[68:71], v[72:75], v[36:51]
	v_mfma_f32_32x32x16_bf16 v[4:19], v[68:71], v[76:79], v[4:19]
	ds_read_b128 v[68:71], v101 offset:18528
	ds_read_b128 v[72:75], v120 offset:55392
	ds_read_b128 v[76:79], v120 offset:60000
	ds_read_b128 v[80:83], v101 offset:23136
	s_waitcnt lgkmcnt(0)
	s_barrier
	v_mfma_f32_32x32x16_bf16 v[52:67], v[68:71], v[72:75], v[52:67]
	v_mfma_f32_32x32x16_bf16 v[20:35], v[68:71], v[76:79], v[20:35]
	v_mfma_f32_32x32x16_bf16 v[36:51], v[80:83], v[72:75], v[36:51]
	v_mfma_f32_32x32x16_bf16 v[4:19], v[80:83], v[76:79], v[4:19]
	s_cbranch_scc0 .LBB0_1430
	s_cmpk_gt_u32 s15, 0x3ff
	s_cbranch_scc0 .LBB0_1427
	s_cmpk_gt_i32 s16, 0x5ff
	s_cbranch_scc0 .LBB0_1424
	s_mov_b64 s[6:7], -1
	s_and_b64 vcc, exec, s[18:19]
	s_cbranch_vccz .LBB0_1421
	s_mul_i32 s7, s51, 0x2f00
	s_mul_hi_i32 s6, s51, 0x2f00
	s_add_u32 s10, s94, s7
	s_addc_u32 s11, s95, s6
	s_lshl_b64 s[6:7], s[16:17], 1
	s_add_u32 s6, s10, s6
	s_addc_u32 s7, s11, s7
	s_add_u32 s10, s6, 0x4e97400
	s_addc_u32 s11, s7, 0
	s_mov_b64 s[6:7], 0
